# MLA context-query units moved from the last eight workgroups (pair consumers) to producer workgroups 32-39
# baseline (speedup 1.0000x reference)
.LBB0_885:
	s_and_b64 vcc, exec, s[38:39]
	s_cbranch_vccz .LBB0_904
	s_load_dword s0, s[84:85], 0x10
	v_readlane_b32 s2, v252, 34
	s_waitcnt lgkmcnt(0)
	s_lshr_b32 s0, s0, 16
	s_cmp_lg_u32 s0, 0
	s_cselect_b64 s[0:1], -1, 0
	s_cmp_lg_u64 s[0:1], 0
	s_addc_u32 s0, s63, 0
	s_movk_i32 s1, 0x140
	s_sub_i32 s1, s2, s1
	s_cmp_gt_u32 s0, 7
	v_readlane_b32 s2, v253, 56
	s_cselect_b32 s0, s1, s2
	s_cmp_gt_u32 s0, 63
	v_readlane_b32 s3, v253, 57
	s_cbranch_scc1 .LBB0_904
	v_readlane_b32 s2, v251, 37
	v_readlane_b32 s3, v251, 38
	s_lshl_b32 s1, s0, 5
	s_nop 0
	v_lshl_add_u64 v[188:189], s[2:3], 0, v[152:153]
	v_readlane_b32 s2, v252, 15
	v_readlane_b32 s3, v252, 16
	s_nop 1
	v_lshl_add_u64 v[190:191], s[2:3], 0, v[152:153]
	s_branch .LBB0_889
